# v25 + the +kstep LDS-DMAs of the P2 and P13 K-loops in saddr form too
# speedup vs baseline: 1.0041x; 1.0015x over previous
.LBB0_425:
	v_add_u32_e32 v140, s67, v143
	ds_read_b128 v[146:149], v140
	ds_read_b128 v[150:153], v140 offset:1024
	ds_read_b128 v[154:157], v140 offset:2048
	ds_read_b128 v[158:161], v140 offset:3072
	v_add_u32_e32 v140, s68, v143
	ds_read_b128 v[162:165], v140
	ds_read_b128 v[166:169], v140 offset:1024
	ds_read_b128 v[170:173], v140 offset:2048
	ds_read_b128 v[174:177], v140 offset:3072
	s_add_i32 s13, s13, 2
	s_lshr_b32 s0, s13, 6
	s_mul_hi_u32 s1, s0, 0x8200000
	s_mul_i32 s0, s0, 0x8200000
	s_add_u32 s0, s46, s0
	s_addc_u32 s1, s47, s1
	s_and_b32 s35, s35, 0x1f00
	s_add_u32 s0, s0, s35
	s_addc_u32 s1, s1, 0
	s_add_u32 s0, s0, 0x100080
	s_addc_u32 s1, s1, 0
	s_add_i32 m0, s43, 0xc000
	ds_read_b128 v[178:181], v145
	ds_read_b128 v[182:185], v145 offset:1024
	ds_read_b128 v[186:189], v145 offset:2048
	ds_read_b128 v[190:193], v145 offset:3072
	ds_read_b128 v[194:197], v145 offset:4096
	ds_read_b128 v[198:201], v145 offset:5120
	ds_read_b128 v[202:205], v145 offset:6144
	global_load_lds_dwordx4 v128, s[0:1]
	s_add_i32 m0, s43, 0xe000
	ds_read_b128 v[206:209], v145 offset:7168
	global_load_lds_dwordx4 v132, s[0:1]
	s_waitcnt vmcnt(8)
	s_waitcnt lgkmcnt(0)
	s_setprio 3
	s_barrier
	v_mfma_f32_16x16x32_bf16 v[124:127], v[146:149], v[178:181], v[124:127]
	v_mfma_f32_16x16x32_bf16 v[120:123], v[154:157], v[178:181], v[120:123]
	v_mfma_f32_16x16x32_bf16 v[116:119], v[146:149], v[186:189], v[116:119]
	v_mfma_f32_16x16x32_bf16 v[108:111], v[154:157], v[186:189], v[108:111]
	v_mfma_f32_16x16x32_bf16 v[100:103], v[146:149], v[194:197], v[100:103]
	v_mfma_f32_16x16x32_bf16 v[92:95], v[154:157], v[194:197], v[92:95]
	v_mfma_f32_16x16x32_bf16 v[84:87], v[146:149], v[202:205], v[84:87]
	v_mfma_f32_16x16x32_bf16 v[76:79], v[154:157], v[202:205], v[76:79]
	v_mfma_f32_16x16x32_bf16 v[124:127], v[150:153], v[182:185], v[124:127]
	v_mfma_f32_16x16x32_bf16 v[120:123], v[158:161], v[182:185], v[120:123]
	v_mfma_f32_16x16x32_bf16 v[116:119], v[150:153], v[190:193], v[116:119]
	v_mfma_f32_16x16x32_bf16 v[108:111], v[158:161], v[190:193], v[108:111]
	v_mfma_f32_16x16x32_bf16 v[100:103], v[150:153], v[198:201], v[100:103]
	v_mfma_f32_16x16x32_bf16 v[92:95], v[158:161], v[198:201], v[92:95]
	v_mfma_f32_16x16x32_bf16 v[84:87], v[150:153], v[206:209], v[84:87]
	v_mfma_f32_16x16x32_bf16 v[76:79], v[158:161], v[206:209], v[76:79]
	s_setprio 0
	s_setprio 3
	v_mfma_f32_16x16x32_bf16 v[112:115], v[162:165], v[178:181], v[112:115]
	v_mfma_f32_16x16x32_bf16 v[104:107], v[170:173], v[178:181], v[104:107]
	v_mfma_f32_16x16x32_bf16 v[96:99], v[162:165], v[186:189], v[96:99]
	v_mfma_f32_16x16x32_bf16 v[88:91], v[170:173], v[186:189], v[88:91]
	v_mfma_f32_16x16x32_bf16 v[80:83], v[162:165], v[194:197], v[80:83]
	v_mfma_f32_16x16x32_bf16 v[72:75], v[170:173], v[194:197], v[72:75]
	v_mfma_f32_16x16x32_bf16 v[68:71], v[162:165], v[202:205], v[68:71]
	v_mfma_f32_16x16x32_bf16 v[64:67], v[170:173], v[202:205], v[64:67]
	v_mfma_f32_16x16x32_bf16 v[112:115], v[166:169], v[182:185], v[112:115]
	v_mfma_f32_16x16x32_bf16 v[104:107], v[174:177], v[182:185], v[104:107]
	v_mfma_f32_16x16x32_bf16 v[96:99], v[166:169], v[190:193], v[96:99]
	v_mfma_f32_16x16x32_bf16 v[88:91], v[174:177], v[190:193], v[88:91]
	v_mfma_f32_16x16x32_bf16 v[80:83], v[166:169], v[198:201], v[80:83]
	v_mfma_f32_16x16x32_bf16 v[72:75], v[174:177], v[198:201], v[72:75]
	v_mfma_f32_16x16x32_bf16 v[68:71], v[166:169], v[206:209], v[68:71]
	v_mfma_f32_16x16x32_bf16 v[64:67], v[174:177], v[206:209], v[64:67]
	s_barrier
	s_setprio 0
	s_add_i32 s0, s67, s59
	s_mov_b32 m0, s0
	ds_read_b128 v[178:181], v145 offset:16384
	ds_read_b128 v[182:185], v145 offset:17408
	ds_read_b128 v[186:189], v145 offset:18432
	ds_read_b128 v[190:193], v145 offset:19456
	ds_read_b128 v[194:197], v145 offset:20480
	global_load_lds_dwordx4 v130, s[52:53]
	s_add_i32 m0, s0, 0x2000
	s_add_u32 s0, s52, 0x100000
	s_addc_u32 s1, s53, 0
	s_add_i32 s35, s68, s59
	global_load_lds_dwordx4 v134, s[52:53]
	s_mov_b32 m0, s35
	s_nop 0
	global_load_lds_dwordx4 v130, s[0:1]
	s_add_i32 m0, s35, 0x2000
	ds_read_b128 v[206:209], v145 offset:23552
	global_load_lds_dwordx4 v134, s[0:1]
	s_mov_b32 m0, s43
	ds_read_b128 v[202:205], v145 offset:22528
	global_load_lds_dwordx4 v128, s[54:55]
	s_mov_b32 m0, s62
	ds_read_b128 v[198:201], v145 offset:21504
	global_load_lds_dwordx4 v132, s[54:55]
	s_waitcnt vmcnt(8)
	s_waitcnt lgkmcnt(0)
	s_setprio 3
	s_barrier
	v_mfma_f32_16x16x32_bf16 v[60:63], v[146:149], v[178:181], v[60:63]
	v_mfma_f32_16x16x32_bf16 v[56:59], v[154:157], v[178:181], v[56:59]
	v_mfma_f32_16x16x32_bf16 v[52:55], v[146:149], v[186:189], v[52:55]
	v_mfma_f32_16x16x32_bf16 v[44:47], v[154:157], v[186:189], v[44:47]
	v_mfma_f32_16x16x32_bf16 v[36:39], v[146:149], v[194:197], v[36:39]
	v_mfma_f32_16x16x32_bf16 v[28:31], v[154:157], v[194:197], v[28:31]
	v_mfma_f32_16x16x32_bf16 v[20:23], v[146:149], v[202:205], v[20:23]
	v_mfma_f32_16x16x32_bf16 v[12:15], v[154:157], v[202:205], v[12:15]
	v_mfma_f32_16x16x32_bf16 v[60:63], v[150:153], v[182:185], v[60:63]
	v_mfma_f32_16x16x32_bf16 v[56:59], v[158:161], v[182:185], v[56:59]
	v_mfma_f32_16x16x32_bf16 v[52:55], v[150:153], v[190:193], v[52:55]
	v_mfma_f32_16x16x32_bf16 v[44:47], v[158:161], v[190:193], v[44:47]
	v_mfma_f32_16x16x32_bf16 v[36:39], v[150:153], v[198:201], v[36:39]
	v_mfma_f32_16x16x32_bf16 v[28:31], v[158:161], v[198:201], v[28:31]
	v_mfma_f32_16x16x32_bf16 v[20:23], v[150:153], v[206:209], v[20:23]
	v_mfma_f32_16x16x32_bf16 v[12:15], v[158:161], v[206:209], v[12:15]
	s_setprio 0
	s_setprio 3
	v_mfma_f32_16x16x32_bf16 v[48:51], v[162:165], v[178:181], v[48:51]
	v_mfma_f32_16x16x32_bf16 v[40:43], v[170:173], v[178:181], v[40:43]
	v_mfma_f32_16x16x32_bf16 v[32:35], v[162:165], v[186:189], v[32:35]
	v_mfma_f32_16x16x32_bf16 v[24:27], v[170:173], v[186:189], v[24:27]
	v_mfma_f32_16x16x32_bf16 v[16:19], v[162:165], v[194:197], v[16:19]
	v_mfma_f32_16x16x32_bf16 v[8:11], v[170:173], v[194:197], v[8:11]
	v_mfma_f32_16x16x32_bf16 v[4:7], v[162:165], v[202:205], v[4:7]
	v_mfma_f32_16x16x32_bf16 v[0:3], v[170:173], v[202:205], v[0:3]
	v_mfma_f32_16x16x32_bf16 v[48:51], v[166:169], v[182:185], v[48:51]
	v_mfma_f32_16x16x32_bf16 v[40:43], v[174:177], v[182:185], v[40:43]
	v_mfma_f32_16x16x32_bf16 v[32:35], v[166:169], v[190:193], v[32:35]
	v_mfma_f32_16x16x32_bf16 v[24:27], v[174:177], v[190:193], v[24:27]
	v_mfma_f32_16x16x32_bf16 v[16:19], v[166:169], v[198:201], v[16:19]
	v_mfma_f32_16x16x32_bf16 v[8:11], v[174:177], v[198:201], v[8:11]
	v_mfma_f32_16x16x32_bf16 v[4:7], v[166:169], v[206:209], v[4:7]
	v_mfma_f32_16x16x32_bf16 v[0:3], v[174:177], v[206:209], v[0:3]
	s_barrier
	s_setprio 0
	s_add_i32 s35, 0, 0x18000
	s_add_i32 s37, 0, 0x1c000
	v_add_u32_e32 v158, s35, v143
	v_add_u32_e32 v174, s37, v143
	ds_read_b128 v[146:149], v158
	ds_read_b128 v[150:153], v158 offset:1024
	ds_read_b128 v[154:157], v158 offset:2048
	ds_read_b128 v[158:161], v158 offset:3072
	ds_read_b128 v[162:165], v174
	ds_read_b128 v[166:169], v174 offset:1024
	ds_read_b128 v[170:173], v174 offset:2048
	ds_read_b128 v[174:177], v174 offset:3072
	s_add_u32 s0, s54, 0x100000
	s_addc_u32 s1, s55, 0
	s_mov_b32 m0, s63
	ds_read_b128 v[178:181], v145 offset:32768
	ds_read_b128 v[182:185], v145 offset:33792
	ds_read_b128 v[186:189], v145 offset:34816
	ds_read_b128 v[190:193], v145 offset:35840
	ds_read_b128 v[194:197], v145 offset:36864
	ds_read_b128 v[198:201], v145 offset:37888
	ds_read_b128 v[202:205], v145 offset:38912
	global_load_lds_dwordx4 v128, s[0:1]
	s_mov_b32 m0, s64
	ds_read_b128 v[206:209], v145 offset:39936
	global_load_lds_dwordx4 v132, s[0:1]
	s_waitcnt vmcnt(8)
	s_waitcnt lgkmcnt(0)
	s_setprio 3
	s_barrier
	v_mfma_f32_16x16x32_bf16 v[124:127], v[146:149], v[178:181], v[124:127]
	v_mfma_f32_16x16x32_bf16 v[120:123], v[154:157], v[178:181], v[120:123]
	v_mfma_f32_16x16x32_bf16 v[116:119], v[146:149], v[186:189], v[116:119]
	v_mfma_f32_16x16x32_bf16 v[108:111], v[154:157], v[186:189], v[108:111]
	v_mfma_f32_16x16x32_bf16 v[100:103], v[146:149], v[194:197], v[100:103]
	v_mfma_f32_16x16x32_bf16 v[92:95], v[154:157], v[194:197], v[92:95]
	v_mfma_f32_16x16x32_bf16 v[84:87], v[146:149], v[202:205], v[84:87]
	v_mfma_f32_16x16x32_bf16 v[76:79], v[154:157], v[202:205], v[76:79]
	v_mfma_f32_16x16x32_bf16 v[124:127], v[150:153], v[182:185], v[124:127]
	v_mfma_f32_16x16x32_bf16 v[120:123], v[158:161], v[182:185], v[120:123]
	v_mfma_f32_16x16x32_bf16 v[116:119], v[150:153], v[190:193], v[116:119]
	v_mfma_f32_16x16x32_bf16 v[108:111], v[158:161], v[190:193], v[108:111]
	v_mfma_f32_16x16x32_bf16 v[100:103], v[150:153], v[198:201], v[100:103]
	v_mfma_f32_16x16x32_bf16 v[92:95], v[158:161], v[198:201], v[92:95]
	v_mfma_f32_16x16x32_bf16 v[84:87], v[150:153], v[206:209], v[84:87]
	v_mfma_f32_16x16x32_bf16 v[76:79], v[158:161], v[206:209], v[76:79]
	s_setprio 0
	s_setprio 3
	v_mfma_f32_16x16x32_bf16 v[112:115], v[162:165], v[178:181], v[112:115]
	v_mfma_f32_16x16x32_bf16 v[104:107], v[170:173], v[178:181], v[104:107]
	v_mfma_f32_16x16x32_bf16 v[96:99], v[162:165], v[186:189], v[96:99]
	v_mfma_f32_16x16x32_bf16 v[88:91], v[170:173], v[186:189], v[88:91]
	v_mfma_f32_16x16x32_bf16 v[80:83], v[162:165], v[194:197], v[80:83]
	v_mfma_f32_16x16x32_bf16 v[72:75], v[170:173], v[194:197], v[72:75]
	v_mfma_f32_16x16x32_bf16 v[68:71], v[162:165], v[202:205], v[68:71]
	v_mfma_f32_16x16x32_bf16 v[64:67], v[170:173], v[202:205], v[64:67]
	v_mfma_f32_16x16x32_bf16 v[112:115], v[166:169], v[182:185], v[112:115]
	v_mfma_f32_16x16x32_bf16 v[104:107], v[174:177], v[182:185], v[104:107]
	v_mfma_f32_16x16x32_bf16 v[96:99], v[166:169], v[190:193], v[96:99]
	v_mfma_f32_16x16x32_bf16 v[88:91], v[174:177], v[190:193], v[88:91]
	v_mfma_f32_16x16x32_bf16 v[80:83], v[166:169], v[198:201], v[80:83]
	v_mfma_f32_16x16x32_bf16 v[72:75], v[174:177], v[198:201], v[72:75]
	v_mfma_f32_16x16x32_bf16 v[68:71], v[166:169], v[206:209], v[68:71]
	v_mfma_f32_16x16x32_bf16 v[64:67], v[174:177], v[206:209], v[64:67]
	s_barrier
	s_setprio 0
	s_add_i32 s0, s35, s59
	s_add_u32 s100, s52, 0x80
	s_addc_u32 s101, s53, 0
	s_mov_b32 m0, s0
	ds_read_b128 v[178:181], v145 offset:49152
	ds_read_b128 v[182:185], v145 offset:50176
	ds_read_b128 v[186:189], v145 offset:51200
	ds_read_b128 v[190:193], v145 offset:52224
	global_load_lds_dwordx4 v130, s[100:101]
	s_add_i32 m0, s0, 0x2000
	s_add_u32 s100, s52, 0x80
	s_addc_u32 s101, s53, 0
	s_add_u32 s0, s52, 0x100080
	s_addc_u32 s1, s53, 0
	s_add_i32 s35, s37, s59
	global_load_lds_dwordx4 v134, s[100:101]
	s_mov_b32 m0, s35
	ds_read_b128 v[206:209], v145 offset:56320
	global_load_lds_dwordx4 v130, s[0:1]
	s_add_i32 m0, s35, 0x2000
	ds_read_b128 v[202:205], v145 offset:55296
	global_load_lds_dwordx4 v134, s[0:1]
	s_add_u32 s100, s54, 0x80
	s_addc_u32 s101, s55, 0
	s_mov_b32 m0, s60
	ds_read_b128 v[198:201], v145 offset:54272
	global_load_lds_dwordx4 v128, s[100:101]
	s_add_u32 s100, s54, 0x80
	s_addc_u32 s101, s55, 0
	s_mov_b32 m0, s65
	ds_read_b128 v[194:197], v145 offset:53248
	global_load_lds_dwordx4 v132, s[100:101]
	s_waitcnt vmcnt(8)
	s_waitcnt lgkmcnt(0)
	s_setprio 3
	s_barrier
	v_mfma_f32_16x16x32_bf16 v[60:63], v[146:149], v[178:181], v[60:63]
	v_mfma_f32_16x16x32_bf16 v[56:59], v[154:157], v[178:181], v[56:59]
	v_mfma_f32_16x16x32_bf16 v[52:55], v[146:149], v[186:189], v[52:55]
	v_mfma_f32_16x16x32_bf16 v[44:47], v[154:157], v[186:189], v[44:47]
	v_mfma_f32_16x16x32_bf16 v[36:39], v[146:149], v[194:197], v[36:39]
	v_mfma_f32_16x16x32_bf16 v[28:31], v[154:157], v[194:197], v[28:31]
	v_mfma_f32_16x16x32_bf16 v[20:23], v[146:149], v[202:205], v[20:23]
	v_mfma_f32_16x16x32_bf16 v[12:15], v[154:157], v[202:205], v[12:15]
	v_mfma_f32_16x16x32_bf16 v[60:63], v[150:153], v[182:185], v[60:63]
	v_mfma_f32_16x16x32_bf16 v[56:59], v[158:161], v[182:185], v[56:59]
	v_mfma_f32_16x16x32_bf16 v[52:55], v[150:153], v[190:193], v[52:55]
	v_mfma_f32_16x16x32_bf16 v[44:47], v[158:161], v[190:193], v[44:47]
	v_mfma_f32_16x16x32_bf16 v[36:39], v[150:153], v[198:201], v[36:39]
	v_mfma_f32_16x16x32_bf16 v[28:31], v[158:161], v[198:201], v[28:31]
	v_mfma_f32_16x16x32_bf16 v[20:23], v[150:153], v[206:209], v[20:23]
	v_mfma_f32_16x16x32_bf16 v[12:15], v[158:161], v[206:209], v[12:15]
	s_setprio 0
	s_setprio 3
	v_mfma_f32_16x16x32_bf16 v[48:51], v[162:165], v[178:181], v[48:51]
	v_mfma_f32_16x16x32_bf16 v[40:43], v[170:173], v[178:181], v[40:43]
	v_mfma_f32_16x16x32_bf16 v[32:35], v[162:165], v[186:189], v[32:35]
	v_mfma_f32_16x16x32_bf16 v[24:27], v[170:173], v[186:189], v[24:27]
	v_mfma_f32_16x16x32_bf16 v[16:19], v[162:165], v[194:197], v[16:19]
	v_mfma_f32_16x16x32_bf16 v[8:11], v[170:173], v[194:197], v[8:11]
	v_mfma_f32_16x16x32_bf16 v[4:7], v[162:165], v[202:205], v[4:7]
	v_mfma_f32_16x16x32_bf16 v[0:3], v[170:173], v[202:205], v[0:3]
	v_mfma_f32_16x16x32_bf16 v[48:51], v[166:169], v[182:185], v[48:51]
	v_mfma_f32_16x16x32_bf16 v[40:43], v[174:177], v[182:185], v[40:43]
	v_mfma_f32_16x16x32_bf16 v[32:35], v[166:169], v[190:193], v[32:35]
	v_mfma_f32_16x16x32_bf16 v[24:27], v[174:177], v[190:193], v[24:27]
	v_mfma_f32_16x16x32_bf16 v[16:19], v[166:169], v[198:201], v[16:19]
	v_mfma_f32_16x16x32_bf16 v[8:11], v[174:177], v[198:201], v[8:11]
	v_mfma_f32_16x16x32_bf16 v[4:7], v[166:169], v[206:209], v[4:7]
	v_mfma_f32_16x16x32_bf16 v[0:3], v[174:177], v[206:209], v[0:3]
	s_barrier
	s_setprio 0
	s_cmpk_gt_u32 s13, 0xa9
	s_mov_b32 s35, s4
	s_cbranch_scc1 .LBB0_432

.LBB0_1974:
	v_add_u32_e32 v0, s65, v182
	v_add_u32_e32 v4, s66, v182
	ds_read_b128 v[24:27], v0
	ds_read_b128 v[28:31], v0 offset:1024
	ds_read_b128 v[16:19], v0 offset:2048
	ds_read_b128 v[20:23], v0 offset:3072
	ds_read_b128 v[8:11], v4
	ds_read_b128 v[12:15], v4 offset:1024
	ds_read_b128 v[0:3], v4 offset:2048
	ds_read_b128 v[4:7], v4 offset:3072
	s_add_i32 s35, s35, 2
	s_lshr_b32 s0, s35, 5
	s_mul_hi_u32 s1, s0, 0x4100000
	s_mul_i32 s0, s0, 0x4100000
	s_add_u32 s0, s46, s0
	s_addc_u32 s1, s47, s1
	s_and_b32 s37, s37, 0xf00
	s_add_u32 s0, s0, s37
	s_addc_u32 s1, s1, 0
	s_add_u32 s0, s0, 0x80080
	s_addc_u32 s1, s1, 0
	s_add_i32 m0, s43, 0xc000
	ds_read_b128 v[172:175], v184
	ds_read_b128 v[176:179], v184 offset:1024
	ds_read_b128 v[186:189], v184 offset:2048
	ds_read_b128 v[190:193], v184 offset:3072
	ds_read_b128 v[194:197], v184 offset:4096
	ds_read_b128 v[198:201], v184 offset:5120
	ds_read_b128 v[210:213], v184 offset:6144
	global_load_lds_dwordx4 v160, s[0:1]
	s_add_i32 m0, s43, 0xe000
	ds_read_b128 v[214:217], v184 offset:7168
	global_load_lds_dwordx4 v164, s[0:1]
	s_waitcnt vmcnt(8)
	s_waitcnt lgkmcnt(0)
	s_setprio 3
	s_barrier
	v_mfma_scale_f32_16x16x128_f8f6f4 v[156:159], v[24:31], v[172:179], v[156:159], v180, v180 op_sel_hi:[0,0,0]
	v_mfma_scale_f32_16x16x128_f8f6f4 v[152:155], v[16:23], v[172:179], v[152:155], v180, v180 op_sel_hi:[0,0,0]
	v_mfma_scale_f32_16x16x128_f8f6f4 v[144:147], v[24:31], v[186:193], v[144:147], v180, v180 op_sel_hi:[0,0,0]
	v_mfma_scale_f32_16x16x128_f8f6f4 v[136:139], v[16:23], v[186:193], v[136:139], v180, v180 op_sel_hi:[0,0,0]
	v_mfma_scale_f32_16x16x128_f8f6f4 v[128:131], v[24:31], v[194:201], v[128:131], v180, v180 op_sel_hi:[0,0,0]
	v_mfma_scale_f32_16x16x128_f8f6f4 v[120:123], v[16:23], v[194:201], v[120:123], v180, v180 op_sel_hi:[0,0,0]
	v_mfma_scale_f32_16x16x128_f8f6f4 v[112:115], v[24:31], v[210:217], v[112:115], v180, v180 op_sel_hi:[0,0,0]
	v_mfma_scale_f32_16x16x128_f8f6f4 v[104:107], v[16:23], v[210:217], v[104:107], v180, v180 op_sel_hi:[0,0,0]
	s_setprio 0
	s_setprio 3
	v_mfma_scale_f32_16x16x128_f8f6f4 v[148:151], v[8:15], v[172:179], v[148:151], v180, v180 op_sel_hi:[0,0,0]
	v_mfma_scale_f32_16x16x128_f8f6f4 v[140:143], v[0:7], v[172:179], v[140:143], v180, v180 op_sel_hi:[0,0,0]
	v_mfma_scale_f32_16x16x128_f8f6f4 v[132:135], v[8:15], v[186:193], v[132:135], v180, v180 op_sel_hi:[0,0,0]
	v_mfma_scale_f32_16x16x128_f8f6f4 v[124:127], v[0:7], v[186:193], v[124:127], v180, v180 op_sel_hi:[0,0,0]
	v_mfma_scale_f32_16x16x128_f8f6f4 v[116:119], v[8:15], v[194:201], v[116:119], v180, v180 op_sel_hi:[0,0,0]
	v_mfma_scale_f32_16x16x128_f8f6f4 v[108:111], v[0:7], v[194:201], v[108:111], v180, v180 op_sel_hi:[0,0,0]
	v_mfma_scale_f32_16x16x128_f8f6f4 v[100:103], v[8:15], v[210:217], v[100:103], v180, v180 op_sel_hi:[0,0,0]
	v_mfma_scale_f32_16x16x128_f8f6f4 v[96:99], v[0:7], v[210:217], v[96:99], v180, v180 op_sel_hi:[0,0,0]
	s_barrier
	s_setprio 0
	s_add_i32 s0, s65, s58
	s_mov_b32 m0, s0
	ds_read_b128 v[186:189], v184 offset:16384
	ds_read_b128 v[190:193], v184 offset:17408
	ds_read_b128 v[194:197], v184 offset:18432
	ds_read_b128 v[198:201], v184 offset:19456
	ds_read_b128 v[210:213], v184 offset:20480
	global_load_lds_dwordx4 v162, s[52:53]
	s_add_i32 m0, s0, 0x2000
	s_add_u32 s0, s52, 0x80000
	s_addc_u32 s1, s53, 0
	s_add_i32 s37, s66, s58
	global_load_lds_dwordx4 v166, s[52:53]
	s_mov_b32 m0, s37
	s_nop 0
	global_load_lds_dwordx4 v162, s[0:1]
	s_add_i32 m0, s37, 0x2000
	ds_read_b128 v[222:225], v184 offset:23552
	global_load_lds_dwordx4 v166, s[0:1]
	s_mov_b32 m0, s43
	ds_read_b128 v[218:221], v184 offset:22528
	global_load_lds_dwordx4 v160, s[54:55]
	s_mov_b32 m0, s59
	ds_read_b128 v[214:217], v184 offset:21504
	global_load_lds_dwordx4 v164, s[54:55]
	s_waitcnt vmcnt(8)
	s_waitcnt lgkmcnt(0)
	s_setprio 3
	s_barrier
	v_mfma_scale_f32_16x16x128_f8f6f4 v[92:95], v[24:31], v[186:193], v[92:95], v180, v180 op_sel_hi:[0,0,0]
	v_mfma_scale_f32_16x16x128_f8f6f4 v[88:91], v[16:23], v[186:193], v[88:91], v180, v180 op_sel_hi:[0,0,0]
	v_mfma_scale_f32_16x16x128_f8f6f4 v[80:83], v[24:31], v[194:201], v[80:83], v180, v180 op_sel_hi:[0,0,0]
	v_mfma_scale_f32_16x16x128_f8f6f4 v[72:75], v[16:23], v[194:201], v[72:75], v180, v180 op_sel_hi:[0,0,0]
	v_mfma_scale_f32_16x16x128_f8f6f4 v[64:67], v[24:31], v[210:217], v[64:67], v180, v180 op_sel_hi:[0,0,0]
	v_mfma_scale_f32_16x16x128_f8f6f4 v[56:59], v[16:23], v[210:217], v[56:59], v180, v180 op_sel_hi:[0,0,0]
	v_mfma_scale_f32_16x16x128_f8f6f4 v[48:51], v[24:31], v[218:225], v[48:51], v180, v180 op_sel_hi:[0,0,0]
	v_mfma_scale_f32_16x16x128_f8f6f4 v[40:43], v[16:23], v[218:225], v[40:43], v180, v180 op_sel_hi:[0,0,0]
	s_setprio 0
	s_setprio 3
	v_mfma_scale_f32_16x16x128_f8f6f4 v[84:87], v[8:15], v[186:193], v[84:87], v180, v180 op_sel_hi:[0,0,0]
	v_mfma_scale_f32_16x16x128_f8f6f4 v[76:79], v[0:7], v[186:193], v[76:79], v180, v180 op_sel_hi:[0,0,0]
	v_mfma_scale_f32_16x16x128_f8f6f4 v[68:71], v[8:15], v[194:201], v[68:71], v180, v180 op_sel_hi:[0,0,0]
	v_mfma_scale_f32_16x16x128_f8f6f4 v[60:63], v[0:7], v[194:201], v[60:63], v180, v180 op_sel_hi:[0,0,0]
	v_mfma_scale_f32_16x16x128_f8f6f4 v[52:55], v[8:15], v[210:217], v[52:55], v180, v180 op_sel_hi:[0,0,0]
	v_mfma_scale_f32_16x16x128_f8f6f4 v[44:47], v[0:7], v[210:217], v[44:47], v180, v180 op_sel_hi:[0,0,0]
	v_mfma_scale_f32_16x16x128_f8f6f4 v[36:39], v[8:15], v[218:225], v[36:39], v180, v180 op_sel_hi:[0,0,0]
	v_mfma_scale_f32_16x16x128_f8f6f4 v[32:35], v[0:7], v[218:225], v[32:35], v180, v180 op_sel_hi:[0,0,0]
	s_barrier
	s_setprio 0
	s_add_i32 s37, 0, 0x18000
	s_add_i32 s56, 0, 0x1c000
	v_add_u32_e32 v12, s37, v182
	v_add_u32_e32 v28, s56, v182
	ds_read_b128 v[0:3], v12
	ds_read_b128 v[4:7], v12 offset:1024
	ds_read_b128 v[8:11], v12 offset:2048
	ds_read_b128 v[12:15], v12 offset:3072
	ds_read_b128 v[16:19], v28
	ds_read_b128 v[20:23], v28 offset:1024
	ds_read_b128 v[24:27], v28 offset:2048
	ds_read_b128 v[28:31], v28 offset:3072
	s_add_u32 s0, s54, 0x80000
	s_addc_u32 s1, s55, 0
	s_mov_b32 m0, s60
	ds_read_b128 v[186:189], v184 offset:32768
	ds_read_b128 v[190:193], v184 offset:33792
	ds_read_b128 v[194:197], v184 offset:34816
	ds_read_b128 v[198:201], v184 offset:35840
	ds_read_b128 v[210:213], v184 offset:36864
	ds_read_b128 v[214:217], v184 offset:37888
	ds_read_b128 v[218:221], v184 offset:38912
	global_load_lds_dwordx4 v160, s[0:1]
	s_mov_b32 m0, s61
	ds_read_b128 v[222:225], v184 offset:39936
	global_load_lds_dwordx4 v164, s[0:1]
	s_waitcnt vmcnt(8)
	s_waitcnt lgkmcnt(0)
	s_setprio 3
	s_barrier
	v_mfma_scale_f32_16x16x128_f8f6f4 v[156:159], v[0:7], v[186:193], v[156:159], v180, v180 op_sel_hi:[0,0,0]
	v_mfma_scale_f32_16x16x128_f8f6f4 v[152:155], v[8:15], v[186:193], v[152:155], v180, v180 op_sel_hi:[0,0,0]
	v_mfma_scale_f32_16x16x128_f8f6f4 v[144:147], v[0:7], v[194:201], v[144:147], v180, v180 op_sel_hi:[0,0,0]
	v_mfma_scale_f32_16x16x128_f8f6f4 v[136:139], v[8:15], v[194:201], v[136:139], v180, v180 op_sel_hi:[0,0,0]
	v_mfma_scale_f32_16x16x128_f8f6f4 v[128:131], v[0:7], v[210:217], v[128:131], v180, v180 op_sel_hi:[0,0,0]
	v_mfma_scale_f32_16x16x128_f8f6f4 v[120:123], v[8:15], v[210:217], v[120:123], v180, v180 op_sel_hi:[0,0,0]
	v_mfma_scale_f32_16x16x128_f8f6f4 v[112:115], v[0:7], v[218:225], v[112:115], v180, v180 op_sel_hi:[0,0,0]
	v_mfma_scale_f32_16x16x128_f8f6f4 v[104:107], v[8:15], v[218:225], v[104:107], v180, v180 op_sel_hi:[0,0,0]
	s_setprio 0
	s_setprio 3
	v_mfma_scale_f32_16x16x128_f8f6f4 v[148:151], v[16:23], v[186:193], v[148:151], v180, v180 op_sel_hi:[0,0,0]
	v_mfma_scale_f32_16x16x128_f8f6f4 v[140:143], v[24:31], v[186:193], v[140:143], v180, v180 op_sel_hi:[0,0,0]
	v_mfma_scale_f32_16x16x128_f8f6f4 v[132:135], v[16:23], v[194:201], v[132:135], v180, v180 op_sel_hi:[0,0,0]
	v_mfma_scale_f32_16x16x128_f8f6f4 v[124:127], v[24:31], v[194:201], v[124:127], v180, v180 op_sel_hi:[0,0,0]
	v_mfma_scale_f32_16x16x128_f8f6f4 v[116:119], v[16:23], v[210:217], v[116:119], v180, v180 op_sel_hi:[0,0,0]
	v_mfma_scale_f32_16x16x128_f8f6f4 v[108:111], v[24:31], v[210:217], v[108:111], v180, v180 op_sel_hi:[0,0,0]
	v_mfma_scale_f32_16x16x128_f8f6f4 v[100:103], v[16:23], v[218:225], v[100:103], v180, v180 op_sel_hi:[0,0,0]
	v_mfma_scale_f32_16x16x128_f8f6f4 v[96:99], v[24:31], v[218:225], v[96:99], v180, v180 op_sel_hi:[0,0,0]
	s_barrier
	s_setprio 0
	s_add_i32 s0, s37, s58
	s_add_u32 s100, s52, 0x80
	s_addc_u32 s101, s53, 0
	s_mov_b32 m0, s0
	ds_read_b128 v[186:189], v184 offset:49152
	ds_read_b128 v[190:193], v184 offset:50176
	ds_read_b128 v[194:197], v184 offset:51200
	ds_read_b128 v[198:201], v184 offset:52224
	global_load_lds_dwordx4 v162, s[100:101]
	s_add_i32 m0, s0, 0x2000
	s_add_u32 s100, s52, 0x80
	s_addc_u32 s101, s53, 0
	s_add_u32 s0, s52, 0x80080
	s_addc_u32 s1, s53, 0
	s_add_i32 s37, s56, s58
	global_load_lds_dwordx4 v166, s[100:101]
	s_mov_b32 m0, s37
	ds_read_b128 v[222:225], v184 offset:56320
	global_load_lds_dwordx4 v162, s[0:1]
	s_add_i32 m0, s37, 0x2000
	ds_read_b128 v[218:221], v184 offset:55296
	global_load_lds_dwordx4 v166, s[0:1]
	s_add_u32 s100, s54, 0x80
	s_addc_u32 s101, s55, 0
	s_mov_b32 m0, s62
	ds_read_b128 v[214:217], v184 offset:54272
	global_load_lds_dwordx4 v160, s[100:101]
	s_add_u32 s100, s54, 0x80
	s_addc_u32 s101, s55, 0
	s_mov_b32 m0, s63
	ds_read_b128 v[210:213], v184 offset:53248
	global_load_lds_dwordx4 v164, s[100:101]
	s_waitcnt vmcnt(8)
	s_waitcnt lgkmcnt(0)
	s_setprio 3
	s_barrier
	v_mfma_scale_f32_16x16x128_f8f6f4 v[92:95], v[0:7], v[186:193], v[92:95], v180, v180 op_sel_hi:[0,0,0]
	v_mfma_scale_f32_16x16x128_f8f6f4 v[88:91], v[8:15], v[186:193], v[88:91], v180, v180 op_sel_hi:[0,0,0]
	v_mfma_scale_f32_16x16x128_f8f6f4 v[80:83], v[0:7], v[194:201], v[80:83], v180, v180 op_sel_hi:[0,0,0]
	v_mfma_scale_f32_16x16x128_f8f6f4 v[72:75], v[8:15], v[194:201], v[72:75], v180, v180 op_sel_hi:[0,0,0]
	v_mfma_scale_f32_16x16x128_f8f6f4 v[64:67], v[0:7], v[210:217], v[64:67], v180, v180 op_sel_hi:[0,0,0]
	v_mfma_scale_f32_16x16x128_f8f6f4 v[56:59], v[8:15], v[210:217], v[56:59], v180, v180 op_sel_hi:[0,0,0]
	v_mfma_scale_f32_16x16x128_f8f6f4 v[48:51], v[0:7], v[218:225], v[48:51], v180, v180 op_sel_hi:[0,0,0]
	v_mfma_scale_f32_16x16x128_f8f6f4 v[40:43], v[8:15], v[218:225], v[40:43], v180, v180 op_sel_hi:[0,0,0]
	s_setprio 0
	s_setprio 3
	v_mfma_scale_f32_16x16x128_f8f6f4 v[84:87], v[16:23], v[186:193], v[84:87], v180, v180 op_sel_hi:[0,0,0]
	v_mfma_scale_f32_16x16x128_f8f6f4 v[76:79], v[24:31], v[186:193], v[76:79], v180, v180 op_sel_hi:[0,0,0]
	v_mfma_scale_f32_16x16x128_f8f6f4 v[68:71], v[16:23], v[194:201], v[68:71], v180, v180 op_sel_hi:[0,0,0]
	v_mfma_scale_f32_16x16x128_f8f6f4 v[60:63], v[24:31], v[194:201], v[60:63], v180, v180 op_sel_hi:[0,0,0]
	v_mfma_scale_f32_16x16x128_f8f6f4 v[52:55], v[16:23], v[210:217], v[52:55], v180, v180 op_sel_hi:[0,0,0]
	v_mfma_scale_f32_16x16x128_f8f6f4 v[44:47], v[24:31], v[210:217], v[44:47], v180, v180 op_sel_hi:[0,0,0]
	v_mfma_scale_f32_16x16x128_f8f6f4 v[36:39], v[16:23], v[218:225], v[36:39], v180, v180 op_sel_hi:[0,0,0]
	v_mfma_scale_f32_16x16x128_f8f6f4 v[32:35], v[24:31], v[218:225], v[32:35], v180, v180 op_sel_hi:[0,0,0]
	s_barrier
	s_setprio 0
	s_cmpk_gt_u32 s35, 0x53
	s_mov_b32 s37, s6
	s_cbranch_scc1 .LBB0_1981
